# 7 of 14 grid barriers replaced by 32-block group barriers (blocks sharing blockIdx%8 on one XCD, verified at run time, global fallback); split-phase global counter guards the P write-after-read
# speedup vs baseline: 1.0190x; 1.0142x over previous
.LBB0_14:
	s_or_b64 exec, exec, s[4:5]
	s_load_dwordx16 s[36:51], s[0:1], 0x40
	s_waitcnt lgkmcnt(0)
	s_barrier
	s_getreg_b32 s8, hwreg(HW_REG_XCC_ID, 0, 4)
	v_writelane_b32 v254, s36, 0
	s_nop 1
	v_writelane_b32 v254, s37, 1
	v_writelane_b32 v254, s38, 2
	v_writelane_b32 v254, s39, 3
	v_writelane_b32 v254, s40, 4
	v_writelane_b32 v254, s41, 5
	v_writelane_b32 v254, s42, 6
	v_writelane_b32 v254, s43, 7
	v_writelane_b32 v254, s44, 8
	v_writelane_b32 v254, s45, 9
	v_writelane_b32 v254, s46, 10
	v_writelane_b32 v254, s47, 11
	v_writelane_b32 v254, s48, 12
	v_writelane_b32 v254, s49, 13
	v_writelane_b32 v254, s50, 14
	v_writelane_b32 v254, s51, 15
	s_and_saveexec_b64 s[4:5], vcc
	s_cbranch_execz .LBB0_17
	s_mov_b64 s[6:7], exec
	v_mbcnt_lo_u32_b32 v0, s6, 0
	v_mbcnt_hi_u32_b32 v0, s7, v0
	v_cmp_eq_u32_e32 vcc, 0, v0
	s_and_b64 s[10:11], exec, vcc
	s_mov_b64 exec, s[10:11]
	s_cbranch_execz .LBB0_17
	s_and_b32 s10, s8, 15
	s_lshl_b32 s10, 1, s10
	s_and_b32 s11, s85, 7
	s_lshl_b32 s11, s11, 2
	s_add_i32 s11, s11, 0xb8fb040
	v_mov_b32_e32 v0, s11
	v_mov_b32_e32 v1, s10
	global_atomic_or v0, v1, s[28:29]
	s_waitcnt vmcnt(0)
	s_lshl_b32 s8, s8, 8
	s_and_b32 s8, s8, 0xf00
	s_add_u32 s8, s28, s8
	s_addc_u32 s9, s29, 0
	s_bcnt1_i32_b64 s6, s[6:7]
	v_mov_b32_e32 v0, 0xb8fb000
	v_mov_b32_e32 v1, s6
	global_atomic_add v0, v1, s[8:9] offset:1024

.LBB0_66:
	s_cmp_eq_u32 s14, 0
	s_cselect_b64 vcc, -1, 0
	s_cmp_eq_u32 s14, 1
	v_cndmask_b32_e32 v16, 0, v15, vcc
	s_cselect_b64 vcc, -1, 0
	s_cmp_eq_u32 s14, 2
	v_cndmask_b32_e32 v16, v16, v0, vcc
	s_cselect_b64 vcc, -1, 0
	s_cmp_eq_u32 s14, 3
	v_cndmask_b32_e32 v16, v16, v1, vcc
	s_cselect_b64 vcc, -1, 0
	s_cmp_eq_u32 s14, 4
	v_cndmask_b32_e32 v16, v16, v2, vcc
	s_cselect_b64 vcc, -1, 0
	s_cmp_eq_u32 s14, 5
	v_cndmask_b32_e32 v16, v16, v3, vcc
	s_cselect_b64 vcc, -1, 0
	s_cmp_eq_u32 s14, 6
	v_cndmask_b32_e32 v16, v16, v4, vcc
	s_cselect_b64 vcc, -1, 0
	s_cmp_eq_u32 s14, 7
	v_cndmask_b32_e32 v16, v16, v5, vcc
	s_cselect_b64 vcc, -1, 0
	s_cmp_eq_u32 s14, 8
	v_cndmask_b32_e32 v16, v16, v6, vcc
	s_cselect_b64 vcc, -1, 0
	s_cmp_eq_u32 s14, 9
	v_cndmask_b32_e32 v16, v16, v7, vcc
	s_cselect_b64 vcc, -1, 0
	s_cmp_eq_u32 s14, 10
	v_cndmask_b32_e32 v16, v16, v8, vcc
	s_cselect_b64 vcc, -1, 0
	s_cmp_eq_u32 s14, 11
	v_cndmask_b32_e32 v16, v16, v9, vcc
	s_cselect_b64 vcc, -1, 0
	s_cmp_eq_u32 s14, 12
	v_cndmask_b32_e32 v16, v16, v10, vcc
	s_cselect_b64 vcc, -1, 0
	s_cmp_eq_u32 s14, 13
	v_cndmask_b32_e32 v16, v16, v11, vcc
	s_cselect_b64 vcc, -1, 0
	s_cmp_eq_u32 s14, 14
	v_cndmask_b32_e32 v16, v16, v12, vcc
	s_cselect_b64 vcc, -1, 0
	s_cmp_eq_u32 s14, 15
	v_cndmask_b32_e32 v16, v16, v13, vcc
	s_cselect_b64 vcc, -1, 0
	v_cndmask_b32_e32 v16, v16, v14, vcc
	v_cmp_ne_u32_e32 vcc, 0, v15
	s_nop 1
	v_cndmask_b32_e64 v15, 0, 1, vcc
	v_cmp_ne_u32_e32 vcc, 0, v0
	s_nop 1
	v_addc_co_u32_e32 v0, vcc, 0, v15, vcc
	v_cmp_ne_u32_e32 vcc, 0, v1
	s_nop 1
	v_cndmask_b32_e64 v1, 0, 1, vcc
	v_cmp_ne_u32_e32 vcc, 0, v2
	v_max_u32_e32 v2, 1, v16
	s_nop 0
	v_addc_co_u32_e32 v0, vcc, v0, v1, vcc
	v_cmp_ne_u32_e32 vcc, 0, v3
	s_nop 1
	v_cndmask_b32_e64 v1, 0, 1, vcc
	v_cmp_ne_u32_e32 vcc, 0, v4
	s_nop 1
	v_addc_co_u32_e32 v0, vcc, v0, v1, vcc
	v_cmp_ne_u32_e32 vcc, 0, v5
	s_nop 1
	v_cndmask_b32_e64 v1, 0, 1, vcc
	v_cmp_ne_u32_e32 vcc, 0, v6
	s_nop 1
	v_addc_co_u32_e32 v0, vcc, v0, v1, vcc
	v_cmp_ne_u32_e32 vcc, 0, v7
	s_nop 1
	v_cndmask_b32_e64 v1, 0, 1, vcc
	v_cmp_ne_u32_e32 vcc, 0, v8
	s_nop 1
	v_addc_co_u32_e32 v0, vcc, v0, v1, vcc
	v_cmp_ne_u32_e32 vcc, 0, v9
	s_nop 1
	v_cndmask_b32_e64 v1, 0, 1, vcc
	v_cmp_ne_u32_e32 vcc, 0, v10
	s_nop 1
	v_addc_co_u32_e32 v0, vcc, v0, v1, vcc
	v_cmp_ne_u32_e32 vcc, 0, v11
	s_nop 1
	v_cndmask_b32_e64 v1, 0, 1, vcc
	v_cmp_ne_u32_e32 vcc, 0, v12
	s_nop 1
	v_addc_co_u32_e32 v0, vcc, v0, v1, vcc
	v_cmp_ne_u32_e32 vcc, 0, v13
	s_nop 1
	v_cndmask_b32_e64 v1, 0, 1, vcc
	v_cmp_ne_u32_e32 vcc, 0, v14
	s_nop 1
	v_addc_co_u32_e32 v0, vcc, v0, v1, vcc
	v_mov_b32_e32 v1, 0x23800
	v_max_u32_e32 v0, 1, v0
	ds_write_b32 v1, v2
	v_mov_b32_e32 v1, 0x23804
	ds_write_b32 v1, v0
	v_mov_b32_e32 v3, 0
	global_load_dwordx4 v[4:7], v3, s[4:5] offset:64 sc1
	global_load_dwordx4 v[8:11], v3, s[4:5] offset:80 sc1
	s_waitcnt vmcnt(0)
	v_add_u32_e32 v12, -1, v4
	v_and_b32_e32 v12, v12, v4
	v_mov_b32_e32 v13, v4
	v_add_u32_e32 v14, -1, v5
	v_and_b32_e32 v14, v14, v5
	v_or_b32_e32 v12, v12, v14
	v_min_u32_e32 v13, v13, v5
	v_add_u32_e32 v14, -1, v6
	v_and_b32_e32 v14, v14, v6
	v_or_b32_e32 v12, v12, v14
	v_min_u32_e32 v13, v13, v6
	v_add_u32_e32 v14, -1, v7
	v_and_b32_e32 v14, v14, v7
	v_or_b32_e32 v12, v12, v14
	v_min_u32_e32 v13, v13, v7
	v_add_u32_e32 v14, -1, v8
	v_and_b32_e32 v14, v14, v8
	v_or_b32_e32 v12, v12, v14
	v_min_u32_e32 v13, v13, v8
	v_add_u32_e32 v14, -1, v9
	v_and_b32_e32 v14, v14, v9
	v_or_b32_e32 v12, v12, v14
	v_min_u32_e32 v13, v13, v9
	v_add_u32_e32 v14, -1, v10
	v_and_b32_e32 v14, v14, v10
	v_or_b32_e32 v12, v12, v14
	v_min_u32_e32 v13, v13, v10
	v_add_u32_e32 v14, -1, v11
	v_and_b32_e32 v14, v14, v11
	v_or_b32_e32 v12, v12, v14
	v_min_u32_e32 v13, v13, v11
	v_cmp_eq_u32_e32 vcc, 0, v12
	s_nop 1
	v_cndmask_b32_e64 v12, 0, 1, vcc
	v_cmp_ne_u32_e32 vcc, 0, v13
	s_nop 1
	v_cndmask_b32_e32 v12, 0, v12, vcc
	s_cmpk_eq_i32 s30, 0x100
	s_cselect_b32 s76, 1, 0
	v_and_b32_e32 v12, s76, v12
	v_mov_b32_e32 v13, 0x23808
	ds_write_b32 v13, v12

.LBB0_478:
	s_mov_b64 s[4:5], 0xb8fb000
	s_getreg_b32 s6, hwreg(HW_REG_XCC_ID, 0, 4)
	v_mbcnt_lo_u32_b32 v0, -1, 0
	v_mbcnt_hi_u32_b32 v0, -1, v0
	s_waitcnt vmcnt(0)
	s_waitcnt lgkmcnt(0)
	v_sub_u32_e32 v0, 0, v0
	v_cmp_eq_u32_e32 vcc, s3, v0
	s_barrier
	s_and_saveexec_b64 s[0:1], vcc
	s_cbranch_execz .LBB0_532
	v_mov_b32_e32 v2, 0x23808
	s_waitcnt vmcnt(0) lgkmcnt(0)
	ds_read_b32 v2, v2
	s_add_u32 s8, s28, s4
	s_addc_u32 s9, s29, s5
	s_waitcnt lgkmcnt(0)
	v_readfirstlane_b32 s10, v2
	s_cmp_eq_u32 s10, 0
	s_cbranch_scc1 .Lgs1_global
	s_and_b32 s10, s85, 7
	s_lshl_b32 s10, s10, 8
	s_add_i32 s10, s10, 0x480
	v_mov_b32_e32 v3, s10
	v_mov_b32_e32 v4, 1
	v_mov_b32_e32 v5, 0x100
	global_atomic_add v5, v4, s[8:9]
	global_atomic_add v6, v3, v4, s[8:9] sc0
	s_waitcnt vmcnt(0)
	v_and_b32_e32 v6, 0xffffffe0, v6
	v_add_u32_e32 v6, 32, v6
	s_mov_b32 s11, 0
.Lgs1_spin:
	global_load_dword v7, v3, s[8:9] sc1
	s_waitcnt vmcnt(0)
	v_cmp_ge_u32_e32 vcc, v7, v6
	s_cbranch_vccnz .Lgs1_got
	s_sleep 1
	s_add_i32 s11, s11, 1
	s_cmp_lt_u32 s11, 0x8000
	s_cbranch_scc1 .Lgs1_spin
.Lgs1_got:
	buffer_inv sc1
	s_waitcnt vmcnt(0)
	s_branch .LBB0_532
.Lgs1_global:
	s_waitcnt vmcnt(0) expcnt(0) lgkmcnt(0)
	ds_read_b32 v2, v253
	ds_read_b32 v0, v246
	s_add_u32 s4, s28, s4
	s_addc_u32 s5, s29, s5
	s_and_b32 s19, s6, 15
	s_waitcnt lgkmcnt(1)
	v_cmp_ne_u32_e32 vcc, 0, v2
	s_cbranch_vccnz .LBB0_494
	s_add_u32 s6, s4, 0x1000
	s_addc_u32 s7, s5, 0
	s_add_u32 s8, s4, 0x1100
	s_addc_u32 s9, s5, 0
	s_add_u32 s10, s4, 0x1200
	s_addc_u32 s11, s5, 0
	s_add_u32 s12, s4, 0x1300
	s_addc_u32 s13, s5, 0
	s_mov_b32 s20, 1
	s_branch .LBB0_482

.LBB0_630:
	s_mov_b64 s[4:5], 0xb8fb000
	s_getreg_b32 s6, hwreg(HW_REG_XCC_ID, 0, 4)
	v_mbcnt_lo_u32_b32 v0, -1, 0
	v_mbcnt_hi_u32_b32 v0, -1, v0
	s_waitcnt vmcnt(0)
	s_waitcnt lgkmcnt(0)
	v_sub_u32_e32 v0, 0, v0
	v_cmp_eq_u32_e32 vcc, s3, v0
	s_barrier
	s_and_saveexec_b64 s[0:1], vcc
	s_cbranch_execz .LBB0_186
	v_mov_b32_e32 v2, 0x23808
	s_waitcnt vmcnt(0) lgkmcnt(0)
	ds_read_b32 v2, v2
	s_add_u32 s8, s28, s4
	s_addc_u32 s9, s29, s5
	s_waitcnt lgkmcnt(0)
	v_readfirstlane_b32 s10, v2
	s_cmp_eq_u32 s10, 0
	s_cbranch_scc1 .Lgs2_global
	s_cmp_eq_u32 s86, 3
	s_cbranch_scc1 .Lgs2_global
	s_and_b32 s10, s85, 7
	s_lshl_b32 s10, s10, 8
	s_add_i32 s10, s10, 0x480
	v_mov_b32_e32 v3, s10
	v_mov_b32_e32 v4, 1
	v_mov_b32_e32 v5, 0x100
	global_atomic_add v6, v3, v4, s[8:9] sc0
	s_waitcnt vmcnt(0)
	v_and_b32_e32 v6, 0xffffffe0, v6
	v_add_u32_e32 v6, 32, v6
	s_mov_b32 s11, 0

.Lgs2_got:
	s_add_i32 s12, s86, 1
	s_lshl_b32 s12, s12, 8
	v_mov_b32_e32 v8, s12
	s_mov_b32 s11, 0
.Lgs2_spin2:
	global_load_dword v7, v5, s[8:9] sc1
	s_waitcnt vmcnt(0)
	v_cmp_ge_u32_e32 vcc, v7, v8
	s_cbranch_vccnz .Lgs2_got2
	s_sleep 1
	s_add_i32 s11, s11, 1
	s_cmp_lt_u32 s11, 0x8000
	s_cbranch_scc1 .Lgs2_spin2
